# p0_rms_and_transposes_handwritten
# speedup vs baseline: 1.0304x; 1.0206x over previous
.Lrms_done:
	s_cmpk_lt_i32 s74, 0x2560
	s_cbranch_scc0 .LBB0_44
	v_and_b32_e32 v64, 63, v181
	v_lshrrev_b32_e32 v65, 6, v181
	v_lshrrev_b32_e32 v88, 2, v181
	v_and_b32_e32 v89, 3, v181
	v_mul_u32_u24_e32 v71, 0x41, v65
	v_add_lshl_u32 v71, v71, v64, 2
	v_mul_u32_u24_e32 v90, 0x820, v89
	v_lshl_add_u32 v90, v88, 2, v90
.Ltr_loop:
	s_sub_i32 s80, s74, 0x2040
	s_movk_i32 s86, 0x400
	s_mov_b32 s92, 0x10a40000
	s_cmpk_lt_u32 s80, 0x420
	s_cselect_b32 s84, s64, s46
	s_cselect_b32 s85, s65, s47
	s_cselect_b32 s86, 0x1010, s86
	s_cselect_b32 s92, 0x10200000, s92
	s_cselect_b64 s[88:89], -1, 0
	s_cselect_b32 s81, 0, 0x420
	s_sub_u32 s80, s80, s81
	s_lshr_b32 s82, s80, 4
	s_and_b32 s83, s80, 15
	s_lshl_b32 s87, s86, 4
	s_add_u32 s92, s20, s92
	s_addc_u32 s93, s21, 0
	v_lshl_add_u32 v66, s82, 6, v64
	v_add_u32_e32 v67, 16, v66
	v_add_u32_e32 v68, 0xfffff800, v66
	v_cmp_gt_u32_e32 vcc, 0x800, v66
	s_nop 1
	v_cndmask_b32_e32 v69, v67, v66, vcc
	v_cmp_gt_u32_e32 vcc, 0x1000, v66
	s_nop 1
	v_cndmask_b32_e32 v69, v68, v69, vcc
	v_cmp_gt_u32_e64 s[90:91], s86, v66
	v_cndmask_b32_e64 v69, v66, v69, s[88:89]
	s_orn2_b64 s[90:91], s[90:91], s[88:89]
	v_lshl_add_u32 v70, s83, 6, v65
	v_mul_lo_u32 v70, v70, s86
	v_add_lshl_u32 v70, v70, v69, 2
	v_mov_b32_e32 v72, 0
	v_mov_b32_e32 v73, 0
	v_mov_b32_e32 v74, 0
	v_mov_b32_e32 v75, 0
	v_mov_b32_e32 v76, 0
	v_mov_b32_e32 v77, 0
	v_mov_b32_e32 v78, 0
	v_mov_b32_e32 v79, 0
	v_mov_b32_e32 v80, 0
	v_mov_b32_e32 v81, 0
	v_mov_b32_e32 v82, 0
	v_mov_b32_e32 v83, 0
	v_mov_b32_e32 v84, 0
	v_mov_b32_e32 v85, 0
	v_mov_b32_e32 v86, 0
	v_mov_b32_e32 v87, 0
	s_mov_b64 vcc, exec
	s_and_b64 exec, exec, s[90:91]
	global_load_dword v72, v70, s[84:85] nt
	v_add_u32_e32 v70, s87, v70
	global_load_dword v73, v70, s[84:85] nt
	v_add_u32_e32 v70, s87, v70
	global_load_dword v74, v70, s[84:85] nt
	v_add_u32_e32 v70, s87, v70
	global_load_dword v75, v70, s[84:85] nt
	v_add_u32_e32 v70, s87, v70
	global_load_dword v76, v70, s[84:85] nt
	v_add_u32_e32 v70, s87, v70
	global_load_dword v77, v70, s[84:85] nt
	v_add_u32_e32 v70, s87, v70
	global_load_dword v78, v70, s[84:85] nt
	v_add_u32_e32 v70, s87, v70
	global_load_dword v79, v70, s[84:85] nt
	v_add_u32_e32 v70, s87, v70
	global_load_dword v80, v70, s[84:85] nt
	v_add_u32_e32 v70, s87, v70
	global_load_dword v81, v70, s[84:85] nt
	v_add_u32_e32 v70, s87, v70
	global_load_dword v82, v70, s[84:85] nt
	v_add_u32_e32 v70, s87, v70
	global_load_dword v83, v70, s[84:85] nt
	v_add_u32_e32 v70, s87, v70
	global_load_dword v84, v70, s[84:85] nt
	v_add_u32_e32 v70, s87, v70
	global_load_dword v85, v70, s[84:85] nt
	v_add_u32_e32 v70, s87, v70
	global_load_dword v86, v70, s[84:85] nt
	v_add_u32_e32 v70, s87, v70
	global_load_dword v87, v70, s[84:85] nt
	s_mov_b64 exec, vcc
	s_barrier
	s_waitcnt vmcnt(0)
	ds_write_b32 v71, v72
	ds_write_b32 v71, v73 offset:1040
	ds_write_b32 v71, v74 offset:2080
	ds_write_b32 v71, v75 offset:3120
	ds_write_b32 v71, v76 offset:4160
	ds_write_b32 v71, v77 offset:5200
	ds_write_b32 v71, v78 offset:6240
	ds_write_b32 v71, v79 offset:7280
	ds_write_b32 v71, v80 offset:8320
	ds_write_b32 v71, v81 offset:9360
	ds_write_b32 v71, v82 offset:10400
	ds_write_b32 v71, v83 offset:11440
	ds_write_b32 v71, v84 offset:12480
	ds_write_b32 v71, v85 offset:13520
	ds_write_b32 v71, v86 offset:14560
	ds_write_b32 v71, v87 offset:15600
	s_waitcnt lgkmcnt(0)
	s_barrier
	ds_read_b32 v72, v90
	ds_read_b32 v73, v90 offset:260
	ds_read_b32 v74, v90 offset:520
	ds_read_b32 v75, v90 offset:780
	ds_read_b32 v76, v90 offset:1040
	ds_read_b32 v77, v90 offset:1300
	ds_read_b32 v78, v90 offset:1560
	ds_read_b32 v79, v90 offset:1820
	ds_read_b32 v80, v90 offset:8320
	ds_read_b32 v81, v90 offset:8580
	ds_read_b32 v82, v90 offset:8840
	ds_read_b32 v83, v90 offset:9100
	ds_read_b32 v84, v90 offset:9360
	ds_read_b32 v85, v90 offset:9620
	ds_read_b32 v86, v90 offset:9880
	ds_read_b32 v87, v90 offset:10140
	v_lshl_add_u32 v91, s82, 6, v88
	v_lshlrev_b32_e32 v91, 11, v91
	v_lshl_add_u32 v91, v89, 4, v91
	s_lshl_b32 s81, s83, 7
	v_add_u32_e32 v91, s81, v91
	s_waitcnt lgkmcnt(0)
	v_cvt_pk_bf16_f32 v92, v72, v73
	v_cvt_pk_bf16_f32 v93, v74, v75
	v_cvt_pk_bf16_f32 v94, v76, v77
	v_cvt_pk_bf16_f32 v95, v78, v79
	v_cvt_pk_bf16_f32 v96, v80, v81
	v_cvt_pk_bf16_f32 v97, v82, v83
	v_cvt_pk_bf16_f32 v98, v84, v85
	v_cvt_pk_bf16_f32 v99, v86, v87
	global_store_dwordx4 v91, v[92:95], s[92:93]
	global_store_dwordx4 v91, v[96:99], s[92:93] offset:64
	s_add_i32 s74, s74, s22
	s_cmpk_lt_i32 s74, 0x2560
	s_cbranch_scc1 .Ltr_loop
	s_branch .LBB0_44
	s_branch .LBB0_18
